# tile-swizzle division by group size replaced by shifts in all 4 GEMM phase heads
# baseline (speedup 1.0000x reference)
.LBB0_122:
	s_add_i32 s35, s35, 1
	v_readlane_b32 s1, v252, 40
	s_mul_i32 s1, s35, s1
	s_mul_hi_u32 s10, s35, s4
	s_add_i32 s10, s10, s1
	s_mul_i32 s1, s35, s4
	s_add_u32 s72, s1, s8
	s_addc_u32 s73, s10, s30
	v_mov_b64_e32 v[0:1], 0xaff
	v_cmp_gt_i64_e64 s[46:47], s[72:73], v[0:1]
	s_and_b64 vcc, exec, s[46:47]
	s_cbranch_vccnz .LBB0_124
	s_ashr_i32 s1, s72, 31
	s_lshr_b32 s1, s1, 29
	s_add_i32 s1, s72, s1
	s_ashr_i32 s10, s1, 3
	s_and_b32 s1, s1, -8
	s_sub_i32 s1, s72, s1
	s_cmp_lt_i32 s1, 0
	s_movk_i32 s11, 0x161
	s_cselect_b32 s11, s11, 0x160
	s_mul_i32 s1, s11, s1
	s_add_i32 s1, s1, s10
	s_mul_hi_i32 s10, s1, 0x2e8ba2e9
	s_lshr_b32 s11, s10, 31
	s_ashr_i32 s10, s10, 5
	s_add_i32 s10, s10, s11
	s_lshl_b32 s11, s10, 3
	s_mulk_i32 s10, 0xb0
	s_sub_i32 s1, s1, s10
	s_lshr_b32 s76, s1, 3
	s_and_b32 s1, s1, 7
	s_add_i32 s78, s1, s11

.LBB0_190:
	s_ashr_i32 s0, s25, 3
	s_add_i32 s0, s33, s0
	s_ashr_i32 s1, s0, 31
	s_lshr_b32 s1, s1, 27
	s_add_i32 s1, s0, s1
	s_ashr_i32 s25, s1, 5
	s_lshl_b32 s27, s25, 3
	s_andn2_b32 s1, s1, 31
	s_sub_i32 s0, s0, s1
	s_lshr_b32 s25, s0, 3
	s_and_b32 s0, s0, 7
	s_add_i32 s36, s27, s0

.LBB0_323:
	s_add_i32 s22, s22, 1
	s_mul_i32 s1, s22, s48
	s_mul_hi_u32 s11, s22, s4
	s_add_i32 s11, s11, s1
	s_mul_i32 s1, s22, s4
	s_add_u32 s50, s1, s20
	s_addc_u32 s51, s11, s82
	v_cmp_gt_i64_e64 s[76:77], s[50:51], v[184:185]
	s_and_b64 vcc, exec, s[76:77]
	s_cbranch_vccnz .LBB0_325
	s_ashr_i32 s1, s50, 31
	s_lshr_b32 s1, s1, 29
	s_add_i32 s1, s50, s1
	s_ashr_i32 s11, s1, 3
	s_and_b32 s1, s1, -8
	s_sub_i32 s1, s50, s1
	s_cmp_lt_i32 s1, 0
	s_movk_i32 s8, 0x61
	s_cselect_b32 s25, s8, 0x60
	s_mul_i32 s1, s25, s1
	s_add_i32 s1, s1, s11
	s_mul_hi_i32 s11, s1, 0x2aaaaaab
	s_lshr_b32 s25, s11, 31
	s_ashr_i32 s11, s11, 3
	s_add_i32 s11, s11, s25
	s_lshl_b32 s25, s11, 3
	s_mul_i32 s11, s11, 48
	s_sub_i32 s1, s1, s11
	s_lshr_b32 s8, s1, 3
	s_and_b32 s1, s1, 7
	s_add_i32 s92, s1, s25

.LBB0_349:
	s_ashr_i32 s25, s25, 3
	s_add_i32 s25, s30, s25
	s_ashr_i32 s27, s25, 31
	s_lshr_b32 s27, s27, 22
	s_add_i32 s27, s25, s27
	s_ashr_i32 s30, s27, 10
	s_lshl_b32 s30, s30, 3
	s_and_b32 s27, s27, 0xfffffc00
	s_sub_i32 s25, s25, s27
	s_lshr_b32 s46, s25, 2
	s_and_b32 s25, s25, 3
	s_add_i32 s85, s30, s25
